# attention: hi-row SGPR base computed before the last QK MFMA (v18 variant)
# baseline (speedup 1.0000x reference)
; #define SBAR() __builtin_amdgcn_sched_barrier(0)
; __device__ __forceinline__ void finishSM(f32x16& p0, f32x16& p1, float alpha, float& l_reg, bf16x8& pa0, bf16x8& pa1, bf16x8& pa2, bf16x8& pa3) {
;   for (int r = 0; r < 16; ++r) p1[r] = __builtin_amdgcn_exp2f(p1[r]);
;   float ps = 0; for (int r = 0; r < 16; ++r) ps += p0[r]; for (int r = 0; r < 16; ++r) ps += p1[r];
;   { auto rr = __builtin_amdgcn_permlane32_swap(__float_as_uint(ps), __float_as_uint(ps), false, false);
;     ps = __uint_as_float(rr[0]) + __uint_as_float(rr[1]); }
;   l_reg = l_reg * alpha + ps;
;     ...
;   PK4(p0, 0, pa0); PK4(p0, 8, pa1); PK4(p1, 0, pa2); PK4(p1, 8, pa3);
; template <typename TQ>
; __device__ __forceinline__ void attn_dense_body(const TQ* __restrict__ Qb, const bf16* __restrict__ Kh, const bf16* __restrict__ Vh,
;                                                 unsigned short* __restrict__ Ob, int seq, char* lds, const int wave_s) {
;     ...
;     SBAR(); qkt(pB0, pB1, (bf16*)((char*)K_lds + SHM_K), qr, r32, hi);
;     finishSM(pA0, pA1, alA, l_reg, pa0, pa1, pa2, pa3); SBAR();
.LBB0_575:
	ds_read_b128 v[64:67], v189 offset:49152
	ds_read_b128 v[68:71], v189 offset:57344
	ds_read_b128 v[210:213], v199 offset:49152
	ds_read_b128 v[214:217], v199 offset:57344
	ds_read_b128 v[240:243], v192 offset:49152
	ds_read_b128 v[244:247], v192 offset:57344
	v_add_f32_e32 v160, v175, v161
	s_waitcnt lgkmcnt(5)
	v_mfma_f32_32x32x16_bf16 v[80:95], v[64:67], v[112:115], 0
	v_add_f32_e32 v160, v162, v160
	v_add_f32_e32 v160, v206, v160
	v_add_f32_e32 v160, v174, v160
	v_add_f32_e32 v160, v209, v160
	v_add_f32_e32 v160, v163, v160
	v_add_f32_e32 v160, v173, v160
	v_add_f32_e32 v160, v169, v160
	s_waitcnt lgkmcnt(4)
	v_mfma_f32_32x32x16_bf16 v[64:79], v[68:71], v[112:115], 0
	v_add_f32_e32 v160, v171, v160
	v_add_f32_e32 v160, v170, v160
	v_add_f32_e32 v160, v172, v160
	v_exp_f32_e32 v158, v158
	v_add_f32_e32 v160, v165, v160
	v_exp_f32_e32 v159, v159
	v_add_f32_e32 v160, v167, v160
	s_waitcnt lgkmcnt(3)
	v_mfma_f32_32x32x16_bf16 v[80:95], v[210:213], v[108:111], v[80:95]
	v_exp_f32_e32 v156, v156
	v_add_f32_e32 v160, v166, v160
	v_exp_f32_e32 v157, v157
	v_add_f32_e32 v160, v168, v160
	v_exp_f32_e32 v152, v152
	v_add_f32_e32 v160, v158, v160
	v_exp_f32_e32 v153, v153
	s_waitcnt lgkmcnt(2)
	v_mfma_f32_32x32x16_bf16 v[64:79], v[214:217], v[108:111], v[64:79]
	ds_read_b128 v[210:213], v191 offset:49152
	ds_read_b128 v[214:217], v191 offset:57344
	v_add_f32_e32 v160, v159, v160
	v_exp_f32_e32 v148, v148
	v_add_f32_e32 v160, v156, v160
	v_exp_f32_e32 v149, v149
	v_add_f32_e32 v160, v157, v160
	v_exp_f32_e32 v146, v146
	s_waitcnt lgkmcnt(3)
	v_mfma_f32_32x32x16_bf16 v[80:95], v[240:243], v[120:123], v[80:95]
	v_add_f32_e32 v160, v152, v160
	v_exp_f32_e32 v147, v147
	v_add_f32_e32 v160, v153, v160
	v_exp_f32_e32 v154, v154
	v_add_f32_e32 v160, v148, v160
	v_exp_f32_e32 v155, v155
	v_add_f32_e32 v160, v149, v160
	s_waitcnt lgkmcnt(2)
	v_mfma_f32_32x32x16_bf16 v[64:79], v[244:247], v[120:123], v[64:79]
	ds_read_b128 v[240:243], v189 offset:49280
	ds_read_b128 v[244:247], v189 offset:57472
	v_exp_f32_e32 v150, v150
	v_add_f32_e32 v160, v146, v160
	v_exp_f32_e32 v151, v151
	v_add_f32_e32 v160, v147, v160
	v_exp_f32_e32 v144, v144
	v_add_f32_e32 v160, v154, v160
	s_waitcnt lgkmcnt(3)
	v_mfma_f32_32x32x16_bf16 v[80:95], v[210:213], v[124:127], v[80:95]
	v_exp_f32_e32 v145, v145
	v_add_f32_e32 v160, v155, v160
	v_add_f32_e32 v160, v150, v160
	v_add_f32_e32 v160, v151, v160
	v_add_f32_e32 v160, v144, v160
	v_add_f32_e32 v203, v145, v160
	s_waitcnt lgkmcnt(2)
	v_mfma_f32_32x32x16_bf16 v[64:79], v[214:217], v[124:127], v[64:79]
	ds_read_b128 v[210:213], v199 offset:49280
	ds_read_b128 v[214:217], v199 offset:57472
	s_waitcnt lgkmcnt(3)
	v_mfma_f32_32x32x16_bf16 v[80:95], v[240:243], v[116:119], v[80:95]
	s_waitcnt lgkmcnt(2)
	v_mfma_f32_32x32x16_bf16 v[64:79], v[244:247], v[116:119], v[64:79]
	ds_read_b128 v[240:243], v192 offset:49280
	ds_read_b128 v[244:247], v192 offset:57472
	s_waitcnt lgkmcnt(3)
	v_mfma_f32_32x32x16_bf16 v[80:95], v[210:213], v[104:107], v[80:95]
	s_waitcnt lgkmcnt(2)
	v_mfma_f32_32x32x16_bf16 v[64:79], v[214:217], v[104:107], v[64:79]
	ds_read_b128 v[210:213], v191 offset:49280
	ds_read_b128 v[214:217], v191 offset:57472
	s_waitcnt lgkmcnt(3)
	v_mfma_f32_32x32x16_bf16 v[80:95], v[240:243], v[100:103], v[80:95]
	s_waitcnt lgkmcnt(2)
	v_mfma_f32_32x32x16_bf16 v[64:79], v[244:247], v[100:103], v[64:79]
	v_cvt_pk_bf16_f32 v160, v161, v175
	v_cvt_pk_bf16_f32 v161, v162, v206
	v_cvt_pk_bf16_f32 v162, v174, v209
	v_cvt_pk_bf16_f32 v163, v163, v173
	v_cvt_pk_bf16_f32 v206, v169, v171
	v_cvt_pk_bf16_f32 v207, v170, v172
	s_waitcnt lgkmcnt(1)
	v_mfma_f32_32x32x16_bf16 v[80:95], v[210:213], v[96:99], v[80:95]
	v_cvt_pk_bf16_f32 v208, v165, v167
	v_cvt_pk_bf16_f32 v209, v166, v168
	v_cvt_pk_bf16_f32 v166, v158, v159
	v_cvt_pk_bf16_f32 v167, v156, v157
	v_cvt_pk_bf16_f32 v168, v152, v153
	s_add_u32 s40, s52, 0x18000
	s_addc_u32 s41, s53, 0
	s_waitcnt lgkmcnt(0)
; #define SBAR() __builtin_amdgcn_sched_barrier(0)
; #define SLOAD(i, k0) do { sr_[i].vs0 = St::ld8(&Vh[(long)((k0) + sr) * LDK + sc]); sr_[i].vs1 = St::ld8(&Vh[(long)((k0) + 32 + sr) * LDK + sc]); \
;     sr_[i].ks0 = St::ld8(&Kh[(long)((k0) + sr) * LDK + sc]); sr_[i].ks1 = St::ld8(&Kh[(long)((k0) + 32 + sr) * LDK + sc]); } while (0)
; #define SWAIT() do { if constexpr (SDEPTH == 2) asm volatile("s_waitcnt vmcnt(4)" ::: "memory"); else asm volatile("s_waitcnt vmcnt(0)" ::: "memory"); } while (0)
; #define RESC(a) do { if (__any((a) < 1.f)) { if (hi == 0) al_l[r32] = (a); asm volatile("s_waitcnt lgkmcnt(0)" ::: "memory"); \
;     for (int d = 0; d < 4; ++d) for (int r = 0; r < 16; ++r) o[d][r] *= al_l[crow(r, hi)]; } } while (0)
; template <int D0> __device__ __forceinline__ void pv_one(f32x16& od, int vb, bf16x8 pa0, bf16x8 pa1, bf16x8 pa2, bf16x8 pa3) {
;   const s16x4 l0 = tr_read<v_rd_off(D0, 0, 0)>(vb), h0 = tr_read<v_rd_off(D0, 0, 1)>(vb), l1 = tr_read<v_rd_off(D0, 1, 0)>(vb), h1 = tr_read<v_rd_off(D0, 1, 1)>(vb);
;   const s16x4 l2 = tr_read<v_rd_off(D0, 2, 0)>(vb), h2 = tr_read<v_rd_off(D0, 2, 1)>(vb), l3 = tr_read<v_rd_off(D0, 3, 0)>(vb), h3 = tr_read<v_rd_off(D0, 3, 1)>(vb);
;   asm volatile("s_waitcnt lgkmcnt(0)" ::: "memory"); SBAR();
;     ...
;   od = __builtin_amdgcn_mfma_f32_32x32x16_bf16(pa0, PK(l0, h0), od, 0, 0, 0);
;   od = __builtin_amdgcn_mfma_f32_32x32x16_bf16(pa1, PK(l1, h1), od, 0, 0, 0);
;   od = __builtin_amdgcn_mfma_f32_32x32x16_bf16(pa2, PK(l2, h2), od, 0, 0, 0);
;   od = __builtin_amdgcn_mfma_f32_32x32x16_bf16(pa3, PK(l3, h3), od, 0, 0, 0);
;     ...
; }
; __device__ __forceinline__ void pv_d0(f32x16* o, int vb, bf16x8 pa0, bf16x8 pa1, bf16x8 pa2, bf16x8 pa3) {
;   pv_one<0>(o[0], vb, pa0, pa1, pa2, pa3); pv_one<1>(o[1], vb, pa0, pa1, pa2, pa3); pv_one<2>(o[2], vb, pa0, pa1, pa2, pa3); pv_one<3>(o[3], vb, pa0, pa1, pa2, pa3);
; template <typename TQ>
; __device__ __forceinline__ void attn_dense_body(const TQ* __restrict__ Qb, const bf16* __restrict__ Kh, const bf16* __restrict__ Vh,
;                                                 unsigned short* __restrict__ Ob, int seq, char* lds, const int wave_s) {
;     ...
;     SLOAD(SO, (j + SDEPTH) * KVBLK); SBAR();
;     pv_d0(o, vb0, pa0, pa1, pa2, pa3); partialSM(pB0, pB1, m_reg, mnB, alB);
;     __syncthreads(); SWAIT(); SWRITE(0, SE);
;     RESC(alB); __syncthreads();
	v_mfma_f32_32x32x16_bf16 v[64:79], v[214:217], v[96:99], v[64:79]
	v_cvt_pk_bf16_f32 v171, v154, v155
	global_load_dwordx4 v[156:159], v176, s[40:41]
	v_cvt_pk_bf16_f32 v169, v148, v149
	global_load_dwordx4 v[152:155], v176, s[40:41] offset:-512
	v_cvt_pk_bf16_f32 v172, v150, v151
	global_load_dwordx4 v[148:151], v176, s[52:53] offset:-512
	v_cvt_pk_bf16_f32 v170, v146, v147
	v_cvt_pk_bf16_f32 v173, v144, v145
	global_load_dwordx4 v[144:147], v176, s[52:53]
	s_add_u32 s52, s52, 0x30000
	s_addc_u32 s53, s53, 0
	ds_read_b64_tr_b16 v[210:211], v184 offset:0
	ds_read_b64_tr_b16 v[212:213], v184 offset:0x800
	ds_read_b64_tr_b16 v[214:215], v184 offset:0x1000
	ds_read_b64_tr_b16 v[216:217], v184 offset:0x1800
	ds_read_b64_tr_b16 v[224:225], v184 offset:0x2000
	ds_read_b64_tr_b16 v[226:227], v184 offset:0x2800
	ds_read_b64_tr_b16 v[228:229], v184 offset:0x3000
	ds_read_b64_tr_b16 v[230:231], v184 offset:0x3800
	s_waitcnt lgkmcnt(0)
	v_mfma_f32_32x32x16_bf16 v[0:15], v[160:163], v[210:213], v[0:15]
	ds_read_b64_tr_b16 v[210:211], v184 offset:0x200
	ds_read_b64_tr_b16 v[212:213], v184 offset:0xa00
	v_mfma_f32_32x32x16_bf16 v[0:15], v[206:209], v[214:217], v[0:15]
	ds_read_b64_tr_b16 v[214:215], v184 offset:0x1200
	ds_read_b64_tr_b16 v[216:217], v184 offset:0x1a00
	v_mfma_f32_32x32x16_bf16 v[0:15], v[166:169], v[224:227], v[0:15]
	ds_read_b64_tr_b16 v[224:225], v184 offset:0x2200
	ds_read_b64_tr_b16 v[226:227], v184 offset:0x2a00
	v_mfma_f32_32x32x16_bf16 v[0:15], v[170:173], v[228:231], v[0:15]
	ds_read_b64_tr_b16 v[228:229], v184 offset:0x3200
	ds_read_b64_tr_b16 v[230:231], v184 offset:0x3a00
	s_waitcnt lgkmcnt(0)
	v_mfma_f32_32x32x16_bf16 v[48:63], v[160:163], v[210:213], v[48:63]
	ds_read_b64_tr_b16 v[210:211], v184 offset:0x400
	ds_read_b64_tr_b16 v[212:213], v184 offset:0xc00
	v_mfma_f32_32x32x16_bf16 v[48:63], v[206:209], v[214:217], v[48:63]
	ds_read_b64_tr_b16 v[214:215], v184 offset:0x1400
	ds_read_b64_tr_b16 v[216:217], v184 offset:0x1c00
	v_mfma_f32_32x32x16_bf16 v[48:63], v[166:169], v[224:227], v[48:63]
	ds_read_b64_tr_b16 v[224:225], v184 offset:0x2400
	ds_read_b64_tr_b16 v[226:227], v184 offset:0x2c00
	v_mfma_f32_32x32x16_bf16 v[48:63], v[170:173], v[228:231], v[48:63]
	ds_read_b64_tr_b16 v[228:229], v184 offset:0x3400
	ds_read_b64_tr_b16 v[230:231], v184 offset:0x3c00
	s_waitcnt lgkmcnt(0)
	v_mfma_f32_32x32x16_bf16 v[32:47], v[160:163], v[210:213], v[32:47]
	ds_read_b64_tr_b16 v[210:211], v184 offset:0x600
	ds_read_b64_tr_b16 v[212:213], v184 offset:0xe00
	v_mfma_f32_32x32x16_bf16 v[32:47], v[206:209], v[214:217], v[32:47]
	ds_read_b64_tr_b16 v[214:215], v184 offset:0x1600
	ds_read_b64_tr_b16 v[216:217], v184 offset:0x1e00
	v_mfma_f32_32x32x16_bf16 v[32:47], v[166:169], v[224:227], v[32:47]
	ds_read_b64_tr_b16 v[224:225], v184 offset:0x2600
	ds_read_b64_tr_b16 v[226:227], v184 offset:0x2e00
	v_mfma_f32_32x32x16_bf16 v[32:47], v[170:173], v[228:231], v[32:47]
	ds_read_b64_tr_b16 v[228:229], v184 offset:0x3600
	ds_read_b64_tr_b16 v[230:231], v184 offset:0x3e00
	s_waitcnt lgkmcnt(0)
	v_mfma_f32_32x32x16_bf16 v[16:31], v[160:163], v[210:213], v[16:31]
	v_max_f32_e32 v160, v80, v81
	v_max3_f32 v160, v160, v82, v83
	v_max3_f32 v160, v160, v84, v85
	v_max3_f32 v160, v160, v86, v87
	v_max3_f32 v160, v160, v88, v89
	v_max3_f32 v160, v160, v90, v91
	v_max3_f32 v160, v160, v92, v93
	v_mfma_f32_32x32x16_bf16 v[16:31], v[206:209], v[214:217], v[16:31]
	v_max3_f32 v160, v160, v94, v95
	v_max3_f32 v160, v160, v64, v65
	v_max3_f32 v160, v160, v66, v67
	v_max3_f32 v160, v160, v68, v69
	v_max3_f32 v160, v160, v70, v71
	v_max3_f32 v160, v160, v72, v73
	v_max3_f32 v160, v160, v74, v75
	v_max3_f32 v160, v160, v76, v77
	v_mfma_f32_32x32x16_bf16 v[16:31], v[166:169], v[224:227], v[16:31]
	v_max3_f32 v160, v160, v78, v79
	v_mov_b32_e32 v161, v160
	s_nop 1
	v_permlane32_swap_b32_e32 v160, v161
	v_max_f32_e32 v160, v160, v161
	v_sub_f32_e32 v161, v160, v164
	v_cmp_ge_f32_e32 vcc, s9, v161
	v_mfma_f32_32x32x16_bf16 v[16:31], v[170:173], v[228:231], v[16:31]
	s_cmp_eq_u64 vcc, exec
	s_cbranch_scc0 .Lattn_slow_a
	v_mov_b32_e32 v205, 1.0
	v_mov_b32_e32 v206, v164
	s_waitcnt vmcnt(4)
	ds_write_b128 v187, v[128:131]
	ds_write_b128 v187, v[136:139] offset:8192
	ds_write_b128 v185, v[132:135] offset:32768
	ds_write_b128 v185, v[140:143] offset:40960
